# stack26 + scan3: end-of-item workgroup barrier removed (post-B2 reads touch only the f32 result tiles, the next item head writes only operand tiles; B1 of the next item still separates result-tile reu
# speedup vs baseline: 1.0011x; 1.0011x over previous
; __device__ __forceinline__ void phase_scan3(Frame& F, int l) {
;     ...
;         {   bf16x8 a_[2];
; #pragma unroll
;             for (int ks = 0; ks < 2; ++ks) a_[ks] = frag(QH, tm, ks, lane);
; #pragma unroll
;             for (int q = 0; q < 2; ++q) { const int tn = tn0 + q; f32x4 acc = {0.f, 0.f, 0.f, 0.f};
; #pragma unroll
;                 for (int ks = 0; ks < 2; ++ks) acc = mma16(frag(SCB, tn, ks, lane), a_[ks], acc);
;                 *(LAS f32x4*)(YF + (16 * tm + fr) * YP + 16 * tn + 4 * fq) = acc; }
;             bf16x8 x_[4];
; #pragma unroll
;             for (int ks = 0; ks < 4; ++ks) x_[ks] = *(const LAS bf16x8*)(XG + (16 * tm + fr) * GP + 32 * ks + 8 * fq);
; #pragma unroll
;             for (int q = 0; q < 2; ++q) { const int tn = tn0 + q; f32x4 acc = {0.f, 0.f, 0.f, 0.f};
; #pragma unroll
;                 for (int ks = 0; ks < 4; ++ks) acc = mma16(*(const LAS bf16x8*)(WG + (16 * tn + fr) * GP + 32 * ks + 8 * fq), x_[ks], acc);
;                 *(LAS f32x4*)(GF + (16 * tm + fr) * YP + 16 * tn + 4 * fq) = acc; }
;         }
;         lds_barrier();
;         {   float y[8], y0[8], vv[8], g[8], ov[8]; unpack8(y0w, y0); unpack8(vw, vv);
;             { const f32x4 ga = *(const LAS f32x4*)(GF + tok * YP + sg * 8), gb = *(const LAS f32x4*)(GF + tok * YP + sg * 8 + 4); g[0] = ga[0]; g[1] = ga[1]; g[2] = ga[2]; g[3] = ga[3]; g[4] = gb[0]; g[5] = gb[1]; g[6] = gb[2]; g[7] = gb[3]; }
;             const f32x4 ya = *(const LAS f32x4*)(YF + tok * YP + sg * 8), yb = *(const LAS f32x4*)(YF + tok * YP + sg * 8 + 4);
;             y[0] = ya[0] + y0[0]; y[1] = ya[1] + y0[1]; y[2] = ya[2] + y0[2]; y[3] = ya[3] + y0[3]; y[4] = yb[0] + y0[4]; y[5] = yb[1] + y0[5]; y[6] = yb[2] + y0[6]; y[7] = yb[3] + y0[7];
;             float s_ = 0.f;
; #pragma unroll
;             for (int j = 0; j < 8; ++j) s_ += y[j];
;             const float mean = sum8(s_) * (1.f / 64.f); float qv = 0.f;
; #pragma unroll
;             for (int j = 0; j < 8; ++j) { y[j] -= mean; qv += y[j] * y[j]; }
;             const float rstd = __builtin_amdgcn_rsqf(sum8(qv) * (1.f / 64.f) + GN_EPS);
; #pragma unroll
;             for (int j = 0; j < 8; ++j) { const float lw_ = (j < 4) ? lw0[j & 3] : lw1[j & 3], lb_ = (j < 4) ? lb0[j & 3] : lb1[j & 3]; ov[j] = (y[j] * rstd * lw_ + lb_ + bon * vv[j]) * g[j]; }
;             *(GAS v4u*)(ARWKV + m * DC + col) = pack8(ov);
;         }
.LBB0_768:
	ds_read_b128 v[84:87], v62
	ds_read_b128 v[92:95], v78 offset:9216
	ds_read_b128 v[108:111], v79 offset:9216
	ds_read_b128 v[88:91], v62 offset:64
	ds_read_b128 v[96:99], v78 offset:9280
	ds_read_b128 v[112:115], v79 offset:9280
	ds_read_b128 v[116:119], v63 offset:35840
	ds_read_b128 v[132:135], v80 offset:53248
	ds_read_b128 v[148:151], v81 offset:53248
	ds_read_b128 v[120:123], v63 offset:35904
	ds_read_b128 v[136:139], v80 offset:53312
	ds_read_b128 v[152:155], v81 offset:53312
	ds_read_b128 v[124:127], v63 offset:35968
	ds_read_b128 v[140:143], v80 offset:53376
	ds_read_b128 v[156:159], v81 offset:53376
	ds_read_b128 v[128:131], v63 offset:36032
	ds_read_b128 v[144:147], v80 offset:53440
	ds_read_b128 v[160:163], v81 offset:53440
	v_add_u32_e32 v180, s82, v63
	v_add_u32_e32 v181, s83, v63
	v_add_u32_e32 v182, s82, v75
	v_add_u32_e32 v0, s83, v75
	v_add_u32_e32 v70, s22, v58
	v_ashrrev_i32_e32 v71, 31, v70
	s_add_i32 s1, s1, s77
	s_add_i32 s0, s0, s84
	s_andn2_b64 vcc, exec, s[18:19]
	v_lshlrev_b32_e32 v100, 16, v37
	v_and_b32_e32 v101, 0xffff0000, v37
	v_lshlrev_b32_e32 v102, 16, v41
	v_and_b32_e32 v103, 0xffff0000, v41
	v_and_b32_e32 v37, 0xffff0000, v40
	s_waitcnt lgkmcnt(15)
	v_mfma_f32_16x16x32_bf16 v[164:167], v[92:95], v[84:87], 0
	v_mfma_f32_16x16x32_bf16 v[168:171], v[108:111], v[84:87], 0
	s_waitcnt lgkmcnt(13)
	v_mfma_f32_16x16x32_bf16 v[164:167], v[96:99], v[88:91], v[164:167]
	s_waitcnt lgkmcnt(12)
	v_mfma_f32_16x16x32_bf16 v[168:171], v[112:115], v[88:91], v[168:171]
	s_waitcnt lgkmcnt(10)
	v_mfma_f32_16x16x32_bf16 v[172:175], v[132:135], v[116:119], 0
	s_waitcnt lgkmcnt(9)
	v_mfma_f32_16x16x32_bf16 v[176:179], v[148:151], v[116:119], 0
	s_waitcnt lgkmcnt(7)
	v_mfma_f32_16x16x32_bf16 v[172:175], v[136:139], v[120:123], v[172:175]
	s_waitcnt lgkmcnt(6)
	v_mfma_f32_16x16x32_bf16 v[176:179], v[152:155], v[120:123], v[176:179]
	s_waitcnt lgkmcnt(4)
	v_mfma_f32_16x16x32_bf16 v[172:175], v[140:143], v[124:127], v[172:175]
	s_waitcnt lgkmcnt(3)
	v_mfma_f32_16x16x32_bf16 v[176:179], v[156:159], v[124:127], v[176:179]
	s_waitcnt lgkmcnt(1)
	v_mfma_f32_16x16x32_bf16 v[172:175], v[144:147], v[128:131], v[172:175]
	s_waitcnt lgkmcnt(0)
	v_mfma_f32_16x16x32_bf16 v[176:179], v[160:163], v[128:131], v[176:179]
	ds_write_b128 v180, v[164:167] offset:18432
	ds_write_b128 v181, v[168:171] offset:18432
	s_nop 6
	ds_write_b128 v182, v[172:175]
	s_nop 0
	ds_write_b128 v0, v[176:179]
	s_waitcnt lgkmcnt(0)
	s_barrier
	ds_read_b128 v[84:87], v76
	ds_read_b128 v[88:91], v76 offset:16
	ds_read_b128 v[92:95], v77 offset:18432
	ds_read_b128 v[96:99], v77 offset:18448
	s_waitcnt lgkmcnt(0)
	v_pk_add_f32 v[98:99], v[98:99], v[100:101]
	v_lshlrev_b32_e32 v100, 16, v36
	v_and_b32_e32 v101, 0xffff0000, v36
	v_lshlrev_b32_e32 v36, 16, v40
	v_pk_add_f32 v[40:41], v[96:97], v[100:101]
	v_lshlrev_b32_e32 v96, 16, v35
	v_and_b32_e32 v97, 0xffff0000, v35
	v_pk_add_f32 v[94:95], v[94:95], v[96:97]
	v_lshlrev_b32_e32 v96, 16, v34
	v_and_b32_e32 v97, 0xffff0000, v34
	v_lshlrev_b32_e32 v100, 16, v39
	v_and_b32_e32 v101, 0xffff0000, v39
	v_lshlrev_b32_e32 v34, 16, v38
	v_and_b32_e32 v35, 0xffff0000, v38
	v_pk_add_f32 v[38:39], v[92:93], v[96:97]
	s_nop 0
	v_add_f32_e32 v0, 0, v38
	v_add_f32_e32 v0, v39, v0
	v_add_f32_e32 v0, v94, v0
	v_add_f32_e32 v0, v95, v0
	v_add_f32_e32 v0, v40, v0
	v_add_f32_e32 v0, v41, v0
	v_add_f32_e32 v0, v98, v0
	v_add_f32_e32 v0, v99, v0
	s_nop 1
	v_add_f32_dpp v0, v0, v0 quad_perm:[1,0,3,2] row_mask:0xf bank_mask:0xf bound_ctrl:1
	s_nop 1
	v_add_f32_dpp v0, v0, v0 quad_perm:[2,3,0,1] row_mask:0xf bank_mask:0xf bound_ctrl:1
	s_nop 1
	v_add_f32_dpp v0, v0, v0 row_half_mirror row_mask:0xf bank_mask:0xf bound_ctrl:1
	v_mul_f32_e32 v0, 0x3c800000, v0
	v_pk_add_f32 v[38:39], v[38:39], v[0:1] op_sel_hi:[1,0] neg_lo:[0,1] neg_hi:[0,1]
	v_pk_add_f32 v[94:95], v[94:95], v[0:1] op_sel_hi:[1,0] neg_lo:[0,1] neg_hi:[0,1]
	v_pk_mul_f32 v[92:93], v[38:39], v[38:39]
	v_pk_mul_f32 v[96:97], v[94:95], v[94:95]
	v_pk_add_f32 v[40:41], v[40:41], v[0:1] op_sel_hi:[1,0] neg_lo:[0,1] neg_hi:[0,1]
	v_pk_add_f32 v[98:99], v[98:99], v[0:1] op_sel_hi:[1,0] neg_lo:[0,1] neg_hi:[0,1]
	v_add_f32_e32 v0, v92, v93
	v_add_f32_e32 v0, v96, v0
	v_pk_mul_f32 v[104:105], v[40:41], v[40:41]
	v_add_f32_e32 v0, v97, v0
	v_add_f32_e32 v0, v104, v0
	v_pk_mul_f32 v[106:107], v[98:99], v[98:99]
	v_add_f32_e32 v0, v105, v0
	v_add_f32_e32 v0, v106, v0
	v_add_f32_e32 v0, v107, v0
	v_mov_b32_e32 v92, 0x3a27c5ac
	s_nop 0
	v_add_f32_dpp v0, v0, v0 quad_perm:[1,0,3,2] row_mask:0xf bank_mask:0xf bound_ctrl:1
	s_nop 1
	v_add_f32_dpp v0, v0, v0 quad_perm:[2,3,0,1] row_mask:0xf bank_mask:0xf bound_ctrl:1
	s_nop 1
	v_add_f32_dpp v0, v0, v0 row_half_mirror row_mask:0xf bank_mask:0xf bound_ctrl:1
	v_fmamk_f32 v0, v0, 0x3c800000, v92
	v_rsq_f32_e32 v0, v0
	s_nop 0
	v_pk_mul_f32 v[38:39], v[38:39], v[0:1] op_sel_hi:[1,0]
	s_waitcnt vmcnt(0)
	v_pk_fma_f32 v[38:39], v[50:51], v[38:39], v[54:55]
	v_pk_mul_f32 v[40:41], v[40:41], v[0:1] op_sel_hi:[1,0]
	v_pk_fma_f32 v[34:35], v[68:69], v[34:35], v[38:39] op_sel_hi:[0,1,1]
	v_pk_mul_f32 v[38:39], v[94:95], v[0:1] op_sel_hi:[1,0]
	v_pk_fma_f32 v[40:41], v[42:43], v[40:41], v[46:47]
	v_pk_fma_f32 v[38:39], v[52:53], v[38:39], v[56:57]
	v_pk_fma_f32 v[36:37], v[68:69], v[36:37], v[40:41] op_sel_hi:[0,1,1]
	v_pk_fma_f32 v[38:39], v[68:69], v[100:101], v[38:39] op_sel_hi:[0,1,1]
	v_pk_mul_f32 v[40:41], v[98:99], v[0:1] op_sel_hi:[1,0]
	v_pk_mul_f32 v[34:35], v[84:85], v[34:35]
	v_pk_mul_f32 v[38:39], v[86:87], v[38:39]
	v_pk_fma_f32 v[40:41], v[44:45], v[40:41], v[48:49]
	v_cvt_pk_bf16_f32 v34, v34, v35
	v_pk_fma_f32 v[40:41], v[68:69], v[102:103], v[40:41] op_sel_hi:[0,1,1]
	v_cvt_pk_bf16_f32 v35, v38, v39
	v_lshlrev_b64 v[38:39], 11, v[70:71]
	v_pk_mul_f32 v[36:37], v[88:89], v[36:37]
	v_pk_mul_f32 v[40:41], v[90:91], v[40:41]
	v_lshl_add_u64 v[38:39], s[10:11], 0, v[38:39]
	v_lshlrev_b32_e32 v0, 1, v83
	v_cvt_pk_bf16_f32 v36, v36, v37
	v_cvt_pk_bf16_f32 v37, v40, v41
	v_lshl_add_u64 v[38:39], v[38:39], 0, v[0:1]
	global_store_dwordx4 v[38:39], v[34:37], off
	s_waitcnt lgkmcnt(0)
	v_mov_b64_e32 v[40:41], v[32:33]
	v_mov_b64_e32 v[36:37], v[28:29]
	v_mov_b64_e32 v[34:35], v[26:27]
	v_mov_b64_e32 v[38:39], v[30:31]
	v_mov_b32_e32 v68, v82
	s_cbranch_vccz .LBB0_778
